# attention tile code: negate+clamp of the logits fused from two VALU ops into one v_min with neg modifier, on top of the P0 change
# speedup vs baseline: 1.0083x; 1.0062x over previous
; #define LAS __attribute__((address_space(3)))
; __device__ __forceinline__ void attn_phase(LAS unsigned char* lds, const bf16_t* Q, const bf16_t* Kb, const bf16_t* VT, const bf16_t* Zs, bf16_t* OZ, int vcu, int G) {
;     const int tid = threadIdx.x, lane = tid & 63, w = __builtin_amdgcn_readfirstlane(tid >> 6), ql = lane & 31, hi = lane >> 5;
;     constexpr float STOP = 5.421010862427522e-20f;
;     LAS unsigned char* KL = lds;
;     LAS unsigned char* VL = lds + 49152;
;     constexpr int NU = BATCH * 16 * (SEQ / 256);
;     u32x4 sk[6], sv[6];
;     ...
;     if (vcu < NU) ATT_LOAD_STAGE(vcu);
.LBB0_536:
	s_cmp_lt_i32 s54, 8
	s_cselect_b64 s[4:5], -1, 0
	s_and_b64 s[70:71], s[4:5], s[0:1]
	s_andn2_b64 vcc, exec, s[70:71]
	s_cbranch_vccnz .LBB0_557
	s_cmpk_gt_i32 s84, 0x3ff
	v_readfirstlane_b32 s0, v0
	s_cbranch_scc1 .LBB0_557
	s_mov_b32 s98, 0x42fc0000
	s_lshr_b32 s85, s0, 6
	s_ashr_i32 s0, s84, 9
	s_lshl_b32 s8, s84, 8
	s_ashr_i32 s1, s0, 31
	s_and_b32 s8, s8, 0x1f00
	s_bfe_u32 s14, s84, 0x40005
	s_lshl_b64 s[4:5], s[0:1], 13
	s_add_i32 s9, s8, 0xffffff80
	s_cmp_lg_u32 s8, 0
	s_cselect_b32 s8, s9, 0
	s_ashr_i32 s9, s8, 31
	s_add_u32 s10, s4, s8
	s_addc_u32 s11, s5, s9
	s_lshl_b32 s4, s14, 7
	v_lshrrev_b32_e32 v146, 3, v0
	s_waitcnt vmcnt(0)
	v_or_b32_e32 v9, 0x200, v0
	s_add_u32 s12, s6, s4
	v_lshlrev_b32_e32 v8, 4, v0
	v_or_b32_e32 v4, s10, v146
	v_mov_b32_e32 v5, s11
	v_lshrrev_b32_e32 v148, 3, v9
	s_addc_u32 s13, s7, 0
	v_and_b32_e32 v144, 0x70, v8
	v_mov_b32_e32 v145, 0
	v_lshlrev_b64 v[6:7], 11, v[4:5]
	v_or_b32_e32 v4, s10, v148
	s_waitcnt lgkmcnt(0)
	v_lshl_add_u64 v[2:3], s[12:13], 0, v[144:145]
	v_lshlrev_b64 v[4:5], 11, v[4:5]
	v_or_b32_e32 v10, 0x400, v0
	v_or_b32_e32 v11, 0x600, v0
	v_lshl_add_u64 v[6:7], v[2:3], 0, v[6:7]
	v_lshl_add_u64 v[4:5], v[2:3], 0, v[4:5]
	v_lshrrev_b32_e32 v150, 3, v10
	v_mov_b32_e32 v151, v145
	v_lshrrev_b32_e32 v152, 3, v11
	v_mov_b32_e32 v153, v145
	global_load_dwordx4 v[66:69], v[6:7], off
	global_load_dwordx4 v[70:73], v[4:5], off
	v_lshl_add_u64 v[4:5], s[10:11], 0, v[150:151]
	v_lshl_add_u64 v[6:7], s[10:11], 0, v[152:153]
	v_lshlrev_b64 v[4:5], 11, v[4:5]
	v_lshlrev_b64 v[6:7], 11, v[6:7]
	v_or_b32_e32 v12, 0x800, v0
	v_or_b32_e32 v13, 0xa00, v0
	v_lshl_add_u64 v[4:5], v[2:3], 0, v[4:5]
	v_lshl_add_u64 v[6:7], v[2:3], 0, v[6:7]
	v_lshrrev_b32_e32 v154, 3, v12
	v_mov_b32_e32 v155, v145
	v_lshrrev_b32_e32 v156, 3, v13
	v_mov_b32_e32 v157, v145
	global_load_dwordx4 v[74:77], v[4:5], off
	global_load_dwordx4 v[78:81], v[6:7], off
	v_lshl_add_u64 v[4:5], s[10:11], 0, v[154:155]
	v_lshl_add_u64 v[6:7], s[10:11], 0, v[156:157]
	v_lshlrev_b64 v[4:5], 11, v[4:5]
	v_lshlrev_b64 v[6:7], 11, v[6:7]
	v_lshl_add_u64 v[4:5], v[2:3], 0, v[4:5]
	v_lshl_add_u64 v[2:3], v[2:3], 0, v[6:7]
	s_lshl_b64 s[0:1], s[0:1], 14
	global_load_dwordx4 v[82:85], v[4:5], off
	global_load_dwordx4 v[86:89], v[2:3], off
	s_add_u32 s5, s68, s0
	v_mul_u32_u24_e32 v2, 0x556, v0
	s_addc_u32 s10, s69, s1
	s_lshl_b64 s[0:1], s[8:9], 1
	v_lshrrev_b32_e32 v2, 16, v2
	s_add_u32 s0, s5, s0
	v_mul_lo_u16_e32 v3, 48, v2
	s_addc_u32 s1, s10, s1
	v_sub_u16_e32 v4, v0, v3
	s_lshl_b32 s5, s14, 21
	v_lshl_or_b32 v2, v2, 15, s5
	v_mov_b32_e32 v3, v145
	v_lshlrev_b16_e32 v4, 3, v4
	v_lshl_add_u64 v[2:3], s[0:1], 0, v[2:3]
	v_lshlrev_b32_e32 v4, 1, v4
	v_mov_b32_e32 v5, v145
	v_lshl_add_u64 v[2:3], v[2:3], 0, v[4:5]
	v_mul_u32_u24_e32 v4, 0x556, v9
	v_lshrrev_b32_e32 v4, 16, v4
	v_mul_lo_u16_e32 v5, 48, v4
	v_sub_u16_e32 v6, v9, v5
	v_lshl_or_b32 v4, v4, 15, s5
	v_mov_b32_e32 v5, v145
	v_lshlrev_b16_e32 v6, 3, v6
	v_lshl_add_u64 v[4:5], s[0:1], 0, v[4:5]
	v_lshlrev_b32_e32 v6, 1, v6
	v_mov_b32_e32 v7, v145
	v_lshl_add_u64 v[4:5], v[4:5], 0, v[6:7]
	global_load_dwordx4 v[94:97], v[2:3], off
	global_load_dwordx4 v[90:93], v[4:5], off
	v_mul_u32_u24_e32 v2, 0x556, v10
	v_lshrrev_b32_e32 v2, 16, v2
	v_mul_lo_u16_e32 v3, 48, v2
	v_sub_u16_e32 v4, v10, v3
	v_lshl_or_b32 v2, v2, 15, s5
	v_mov_b32_e32 v3, v145
	v_lshlrev_b16_e32 v4, 3, v4
	v_lshl_add_u64 v[2:3], s[0:1], 0, v[2:3]
	v_lshlrev_b32_e32 v4, 1, v4
	v_mov_b32_e32 v5, v145
	v_lshl_add_u64 v[2:3], v[2:3], 0, v[4:5]
	v_mul_u32_u24_e32 v4, 0x556, v11
	v_lshrrev_b32_e32 v4, 16, v4
	v_mul_lo_u16_e32 v5, 48, v4
	v_sub_u16_e32 v6, v11, v5
	v_lshl_or_b32 v4, v4, 15, s5
	v_mov_b32_e32 v5, v145
	v_lshlrev_b16_e32 v6, 3, v6
	v_lshl_add_u64 v[4:5], s[0:1], 0, v[4:5]
	v_lshlrev_b32_e32 v6, 1, v6
	v_lshl_add_u64 v[4:5], v[4:5], 0, v[6:7]
	global_load_dwordx4 v[102:105], v[2:3], off
	global_load_dwordx4 v[98:101], v[4:5], off
	v_mul_u32_u24_e32 v2, 0xaab, v12
	v_lshrrev_b32_e32 v2, 17, v2
	v_mul_lo_u16_e32 v3, 48, v2
	v_sub_u16_e32 v4, v12, v3
	v_lshl_or_b32 v2, v2, 15, s5
	v_mov_b32_e32 v3, v145
	v_lshlrev_b16_e32 v4, 3, v4
	v_lshl_add_u64 v[2:3], s[0:1], 0, v[2:3]
	v_lshlrev_b32_e32 v4, 1, v4
	v_mov_b32_e32 v5, v145
	v_lshl_add_u64 v[2:3], v[2:3], 0, v[4:5]
	v_mul_u32_u24_e32 v4, 0xaab, v13
	v_lshrrev_b32_e32 v4, 17, v4
	v_mul_lo_u16_e32 v5, 48, v4
	v_sub_u16_e32 v6, v13, v5
	v_lshl_or_b32 v4, v4, 15, s5
	v_mov_b32_e32 v5, v145
	v_lshlrev_b16_e32 v6, 3, v6
	v_lshl_add_u64 v[4:5], s[0:1], 0, v[4:5]
	v_lshlrev_b32_e32 v6, 1, v6
	v_lshl_add_u64 v[4:5], v[4:5], 0, v[6:7]
	global_load_dwordx4 v[110:113], v[2:3], off
	global_load_dwordx4 v[106:109], v[4:5], off
	s_movk_i32 s5, 0x3f80
	v_mov_b32_e32 v6, 0x2000
	v_bitop3_b32 v7, v8, s5, v6 bitop3:0xc8
; #define LAS __attribute__((address_space(3)))
; __device__ __forceinline__ void attn_phase(LAS unsigned char* lds, const bf16_t* Q, const bf16_t* Kb, const bf16_t* VT, const bf16_t* Zs, bf16_t* OZ, int vcu, int G) {
;     ...
;         for (int i = 0; i < 6; ++i) { const int idx = tid + NTHR * i, r = idx >> 3, c = idx & 7;
;             *(LAS u32x4*)(KL + r * 128 + ((c ^ ((r >> 1) & 7)) << 4)) = sk[i]; }
; #pragma unroll
;         for (int i = 0; i < 6; ++i) { const int idx = tid + NTHR * i, d = idx / 48, ch = idx % 48;
;             { u32x4 v = sv[i]; const int gp = (2 * ch) ^ (d & 31);
;                 if (d & 1) { const u32x4 t = v; v.x = t.z; v.y = t.w; v.z = t.x; v.w = t.y; }
;                 *(LAS u32x4*)(VL + d * 768 + ((gp & ~1) << 3)) = v; } }
	s_movk_i32 s5, 0x7f80
	v_mov_b32_e32 v6, 0x6000
	v_bitop3_b32 v15, v8, s5, v6 bitop3:0xc8
	s_mov_b32 s5, 0xbf80
	v_mov_b32_e32 v6, 0xa000
	s_mov_b32 s12, 0x5555556
	s_movk_i32 s4, 0x70
	v_bitop3_b32 v17, v8, s5, v6 bitop3:0xc8
	v_mul_hi_u32 v6, v0, s12
	v_bitop3_b32 v3, v8, s4, v0 bitop3:0x48
	v_and_b32_e32 v5, 0x1f80, v8
	v_mul_u32_u24_e32 v8, 48, v6
	v_sub_u32_e32 v8, v0, v8
	v_and_b32_e32 v14, 1, v6
	v_cmp_eq_u32_e64 s[48:49], 0, v14
	v_lshlrev_b32_e32 v14, 4, v8
	v_lshlrev_b32_e32 v16, 3, v6
	v_bitop3_b32 v19, v16, v14, s4 bitop3:0x6c
	v_mul_hi_u32 v14, v9, s12
	v_mul_u32_u24_e32 v16, 48, v14
	v_bfe_u32 v1, v0, 5, 1
	v_sub_u32_e32 v9, v9, v16
	v_and_b32_e32 v16, 1, v14
	v_lshlrev_b32_e32 v4, 2, v1
	s_movk_i32 s14, 0x300
	v_cmp_eq_u32_e64 s[4:5], 0, v16
	v_lshlrev_b32_e32 v16, 4, v9
	v_lshlrev_b32_e32 v21, 3, v14
	s_movk_i32 s15, 0xf0
	v_and_b32_e32 v142, 31, v0
	v_mad_u32_u24 v18, v6, s14, 0
	v_bitop3_b32 v21, v21, v16, s15 bitop3:0x6c
	v_mul_hi_u32 v16, v10, s12
	v_lshlrev_b32_e32 v196, 14, v6
	v_lshlrev_b32_e32 v6, 3, v8
	v_lshlrev_b32_e32 v8, 3, v9
	v_or_b32_e32 v9, 1, v4
	v_mul_u32_u24_e32 v22, 48, v16
	v_cmp_lt_u32_e64 s[16:17], v9, v142
	v_or_b32_e32 v9, 2, v4
	v_sub_u32_e32 v10, v10, v22
	v_cmp_lt_u32_e64 s[18:19], v9, v142
	v_or_b32_e32 v9, 3, v4
	v_lshlrev_b32_e32 v23, 4, v10
	v_lshlrev_b32_e32 v24, 3, v16
	v_cmp_lt_u32_e64 s[20:21], v9, v142
	v_or_b32_e32 v9, 8, v4
	v_bitop3_b32 v23, v24, v23, s15 bitop3:0x6c
	v_mul_hi_u32 v24, v11, s12
	v_cmp_lt_u32_e64 s[22:23], v9, v142
	v_or_b32_e32 v9, 9, v4
	v_mul_u32_u24_e32 v25, 48, v24
	v_cmp_lt_u32_e64 s[24:25], v9, v142
	v_or_b32_e32 v9, 10, v4
	v_sub_u32_e32 v11, v11, v25
	v_cmp_lt_u32_e64 s[26:27], v9, v142
	v_or_b32_e32 v9, 11, v4
	v_lshlrev_b32_e32 v26, 4, v11
	v_lshlrev_b32_e32 v27, 3, v24
	v_cmp_lt_u32_e64 s[28:29], v9, v142
	v_or_b32_e32 v9, 16, v4
	v_bitop3_b32 v26, v27, v26, s15 bitop3:0x6c
	v_mul_hi_u32 v27, v12, s12
	v_cmp_lt_u32_e64 s[30:31], v9, v142
	v_or_b32_e32 v9, 17, v4
	v_mul_u32_u24_e32 v28, 48, v27
	v_cmp_lt_u32_e64 s[34:35], v9, v142
	v_or_b32_e32 v9, 18, v4
	v_sub_u32_e32 v28, v12, v28
	v_and_b32_e32 v12, 1, v27
	v_cmp_lt_u32_e64 s[36:37], v9, v142
	v_or_b32_e32 v9, 19, v4
	v_cmp_eq_u32_e64 s[10:11], 0, v12
	v_lshlrev_b32_e32 v12, 4, v28
	v_lshlrev_b32_e32 v30, 3, v27
	v_mul_hi_u32 v31, v13, s12
	v_cmp_lt_u32_e64 s[38:39], v9, v142
	v_or_b32_e32 v9, 24, v4
	v_bitop3_b32 v30, v30, v12, s15 bitop3:0x6c
	v_mul_u32_u24_e32 v12, 48, v31
	v_cmp_lt_u32_e64 s[40:41], v9, v142
	v_or_b32_e32 v9, 25, v4
	v_sub_u32_e32 v13, v13, v12
	v_and_b32_e32 v12, 1, v31
	v_cmp_lt_u32_e64 s[42:43], v9, v142
	v_or_b32_e32 v9, 26, v4
	s_lshl_b32 s58, s85, 12
	v_lshlrev_b32_e32 v2, 3, v1
	v_lshl_add_u64 v[158:159], s[6:7], 0, v[144:145]
	v_lshlrev_b32_e32 v144, 4, v1
	v_and_b32_e32 v22, 1, v16
	v_and_b32_e32 v25, 1, v24
	v_cmp_eq_u32_e64 s[12:13], 0, v12
	v_lshlrev_b32_e32 v12, 4, v13
	v_lshlrev_b32_e32 v33, 3, v31
	v_cmp_lt_u32_e64 s[44:45], v9, v142
	v_or_b32_e32 v9, 27, v4
	s_add_i32 s58, s58, 0
	v_add_u32_e32 v3, 0, v3
	v_lshl_add_u64 v[160:161], s[6:7], 0, v[144:145]
	v_mad_u32_u24 v20, v14, s14, 0
	v_cmp_eq_u32_e64 s[6:7], 0, v22
	v_mad_u32_u24 v22, v16, s14, 0
	v_cmp_eq_u32_e64 s[8:9], 0, v25
	v_mad_u32_u24 v25, v24, s14, 0
	v_mad_u32_u24 v29, v27, s14, 0
	v_mad_u32_u24 v32, v31, s14, 0
	v_bitop3_b32 v33, v33, v12, s15 bitop3:0x6c
	v_lshlrev_b32_e32 v197, 14, v14
	v_lshlrev_b32_e32 v198, 14, v16
	v_lshlrev_b32_e32 v10, 3, v10
	v_lshlrev_b32_e32 v12, 3, v11
	v_lshlrev_b32_e32 v14, 3, v28
	v_lshlrev_b32_e32 v16, 3, v13
	v_mad_u32_u24 v202, v142, s14, 0
	v_cmp_lt_u32_e64 s[46:47], v9, v142
	v_lshl_add_u32 v9, v142, 7, s58
	v_lshlrev_b32_e32 v144, 1, v2
	v_mbcnt_lo_u32_b32 v2, -1, 0
	s_mov_b32 s73, 0
	v_or_b32_e32 v143, 2, v1
	v_or_b32_e32 v147, 4, v1
	v_or_b32_e32 v149, 6, v1
	v_cmp_eq_u32_e64 s[0:1], 0, v1
	v_lshlrev_b32_e32 v199, 14, v24
	v_lshlrev_b32_e32 v200, 14, v27
	v_lshlrev_b32_e32 v201, 14, v31
	v_add_u32_e32 v203, 0xc000, v202
	v_cmp_lt_u32_e64 s[14:15], v4, v142
	s_add_i32 s86, s85, 1
	s_lshl_b32 s87, s85, 5
	v_or_b32_e32 v204, 0xffffffe0, v142
	v_add_u32_e32 v205, 0xfffff000, v9
	v_lshlrev_b32_e32 v162, 1, v4
	v_add_u32_e32 v206, v3, v5
	v_add_u32_e32 v207, v3, v7
	v_add_u32_e32 v208, v3, v15
	v_add_u32_e32 v209, v3, v17
	v_add_u32_e32 v210, v18, v19
	v_add_u32_e32 v211, v20, v21
	v_add_u32_e32 v212, v22, v23
	v_add_u32_e32 v213, v25, v26
	v_add_u32_e32 v214, v29, v30
	v_add_u32_e32 v215, v32, v33
	v_lshlrev_b32_e32 v164, 1, v6
	v_lshlrev_b32_e32 v166, 1, v8
	v_lshlrev_b32_e32 v168, 1, v10
	v_lshlrev_b32_e32 v170, 1, v12
	v_lshlrev_b32_e32 v172, 1, v14
	v_lshlrev_b32_e32 v174, 1, v16
	s_mov_b32 s88, 0x1f800000
	v_mbcnt_hi_u32_b32 v216, -1, v2
	s_mov_b32 s89, s84
	s_branch .LBB0_540

; #define LAS __attribute__((address_space(3)))
; __device__ __forceinline__ void attn_phase(LAS unsigned char* lds, const bf16_t* Q, const bf16_t* Kb, const bf16_t* VT, const bf16_t* Zs, bf16_t* OZ, int vcu, int G) {
;     ...
;     for (int unit = vcu; unit < NU; unit += G) {
;         ATT_DECODE(unit, h, rowbase, q0b, kw0)
;         const int qblk = unit & 31;
;         const int qb = 8 * qblk + w, q0 = 32 * qb;
;         bf16x8 qf[4];
;         { const bf16_t* qp = Q + (rowbase + q0 + ql) * D + h * 64 + 8 * hi;
; #pragma unroll
;           for (int kk = 0; kk < 4; ++kk) qf[kk] = *(const bf16x8*)(qp + 16 * kk); }
;         u32x2 zz[8];
;         { const bf16_t* zp = Zs + (rowbase + q0 + ql) * D + h * 64 + 4 * hi;
; #pragma unroll
;           for (int g4 = 0; g4 < 4; ++g4) { zz[g4] = *(const u32x2*)(zp + 8 * g4); zz[4 + g4] = *(const u32x2*)(zp + 32 + 8 * g4); } }
;         asm volatile("" ::: "memory");
; #pragma unroll
;         for (int i = 0; i < 6; ++i) { const int idx = tid + NTHR * i, r = idx >> 3, c = idx & 7;
;             *(LAS u32x4*)(KL + r * 128 + ((c ^ ((r >> 1) & 7)) << 4)) = sk[i]; }
; #pragma unroll
;         for (int i = 0; i < 6; ++i) { const int idx = tid + NTHR * i, d = idx / 48, ch = idx % 48;
;             { u32x4 v = sv[i]; const int gp = (2 * ch) ^ (d & 31);
;                 if (d & 1) { const u32x4 t = v; v.x = t.z; v.y = t.w; v.z = t.x; v.w = t.y; }
;                 *(LAS u32x4*)(VL + d * 768 + ((gp & ~1) << 3)) = v; } }
;         __syncthreads();
;         { const int nu_ = unit + G < NU ? unit + G : unit; ATT_LOAD_STAGE(nu_); }
.LBB0_540:
	s_ashr_i32 s74, s84, 9
	s_ashr_i32 s75, s74, 31
	s_and_b32 s58, s84, 31
	s_lshl_b64 s[78:79], s[74:75], 13
	s_lshl_b32 s74, s58, 3
	s_and_b32 s59, s89, 31
	s_lshl_b32 s81, s58, 8
	s_add_i32 s90, s74, s85
	s_lshl_b32 s91, s59, 3
	s_addk_i32 s81, 0xff80
	s_lshl_b32 s80, s90, 5
	s_add_u32 s74, s78, s80
	s_addc_u32 s75, s79, 0
	v_or_b32_e32 v190, s74, v142
	s_lshl_b32 s74, s84, 1
	s_and_b32 s92, s74, 0x3c0
	s_mov_b32 s72, s84
	s_lshl_b32 s76, s92, 1
	s_add_i32 s84, s84, s3
	v_mov_b32_e32 v191, s75
	s_cmpk_gt_i32 s84, 0x3ff
	v_lshlrev_b64 v[2:3], 11, v[190:191]
	s_cselect_b64 s[74:75], -1, 0
	s_cmpk_lt_i32 s84, 0x400
	v_lshl_add_u64 v[4:5], s[64:65], 0, v[2:3]
	s_mov_b32 s77, s73
	v_lshl_add_u64 v[2:3], s[66:67], 0, v[2:3]
	s_cselect_b32 s72, s84, s72
	v_lshl_add_u64 v[4:5], v[4:5], 0, s[76:77]
	v_lshl_add_u64 v[2:3], v[2:3], 0, s[76:77]
	v_mov_b32_e32 v163, v145
	s_bfe_u32 s77, s72, 0x40005
	s_ashr_i32 s82, s72, 9
	s_lshl_b32 s72, s72, 8
	v_lshl_add_u64 v[4:5], v[4:5], 0, v[144:145]
	v_lshl_add_u64 v[2:3], v[2:3], 0, v[162:163]
	s_ashr_i32 s83, s82, 31
	s_and_b32 s72, s72, 0x1f00
	global_load_dwordx4 v[114:117], v[4:5], off
	global_load_dwordx4 v[118:121], v[4:5], off offset:32
	global_load_dwordx4 v[122:125], v[4:5], off offset:64
	global_load_dwordx4 v[126:129], v[4:5], off offset:96
	global_load_dwordx2 v[192:193], v[2:3], off
	global_load_dwordx2 v[186:187], v[2:3], off offset:16
	global_load_dwordx2 v[182:183], v[2:3], off offset:32
	global_load_dwordx2 v[178:179], v[2:3], off offset:48
	global_load_dwordx2 v[188:189], v[2:3], off offset:64
	global_load_dwordx2 v[184:185], v[2:3], off offset:80
	global_load_dwordx2 v[180:181], v[2:3], off offset:96
	global_load_dwordx2 v[176:177], v[2:3], off offset:112
	s_waitcnt vmcnt(17)
	v_cndmask_b32_e64 v5, v95, v97, s[48:49]
	v_cndmask_b32_e64 v4, v94, v96, s[48:49]
	v_cndmask_b32_e64 v3, v97, v95, s[48:49]
	v_cndmask_b32_e64 v2, v96, v94, s[48:49]
	s_lshl_b64 s[94:95], s[82:83], 13
	s_add_i32 s93, s72, 0xffffff80
	ds_write_b128 v206, v[66:69]
	ds_write_b128 v207, v[70:73]
	ds_write_b128 v206, v[74:77] offset:16384
	ds_write_b128 v208, v[78:81]
	ds_write_b128 v206, v[82:85] offset:32768
	ds_write_b128 v209, v[86:89]
	ds_write_b128 v210, v[2:5] offset:49152
	s_waitcnt vmcnt(16)
	v_cndmask_b32_e64 v5, v91, v93, s[4:5]
	v_cndmask_b32_e64 v4, v90, v92, s[4:5]
	v_cndmask_b32_e64 v3, v93, v91, s[4:5]
	v_cndmask_b32_e64 v2, v92, v90, s[4:5]
	s_cmp_lg_u32 s72, 0
	ds_write_b128 v211, v[2:5] offset:49152
	s_waitcnt vmcnt(15)
	v_cndmask_b32_e64 v5, v103, v105, s[6:7]
	v_cndmask_b32_e64 v4, v102, v104, s[6:7]
	v_cndmask_b32_e64 v3, v105, v103, s[6:7]
	v_cndmask_b32_e64 v2, v104, v102, s[6:7]
	s_cselect_b32 s96, s93, 0
	ds_write_b128 v212, v[2:5] offset:49152
	s_waitcnt vmcnt(14)
	v_cndmask_b32_e64 v5, v99, v101, s[8:9]
	v_cndmask_b32_e64 v4, v98, v100, s[8:9]
	v_cndmask_b32_e64 v3, v101, v99, s[8:9]
	v_cndmask_b32_e64 v2, v100, v98, s[8:9]
	s_ashr_i32 s97, s96, 31
	ds_write_b128 v213, v[2:5] offset:49152
	s_waitcnt vmcnt(13)
	v_cndmask_b32_e64 v5, v111, v113, s[10:11]
	v_cndmask_b32_e64 v4, v110, v112, s[10:11]
	v_cndmask_b32_e64 v3, v113, v111, s[10:11]
	v_cndmask_b32_e64 v2, v112, v110, s[10:11]
	s_add_u32 s94, s94, s96
	ds_write_b128 v214, v[2:5] offset:49152
	s_waitcnt vmcnt(12)
	v_cndmask_b32_e64 v5, v107, v109, s[12:13]
	v_cndmask_b32_e64 v4, v106, v108, s[12:13]
	v_cndmask_b32_e64 v3, v109, v107, s[12:13]
	v_cndmask_b32_e64 v2, v108, v106, s[12:13]
	s_addc_u32 s95, s95, s97
	ds_write_b128 v215, v[2:5] offset:49152
	s_lshl_b32 s72, s77, 7
	v_mov_b32_e32 v5, s95
	v_or_b32_e32 v4, s94, v146
	v_mov_b32_e32 v7, s95
	v_or_b32_e32 v6, s94, v148
	v_lshl_add_u64 v[2:3], v[158:159], 0, s[72:73]
	v_lshlrev_b64 v[4:5], 11, v[4:5]
	v_lshlrev_b64 v[6:7], 11, v[6:7]
	v_lshl_add_u64 v[4:5], v[2:3], 0, v[4:5]
	v_lshl_add_u64 v[6:7], v[2:3], 0, v[6:7]
	s_waitcnt lgkmcnt(0)
	s_barrier
	global_load_dwordx4 v[66:69], v[4:5], off
	global_load_dwordx4 v[70:73], v[6:7], off
	v_lshl_add_u64 v[4:5], s[94:95], 0, v[150:151]
	v_lshl_add_u64 v[6:7], s[94:95], 0, v[152:153]
	v_lshlrev_b64 v[4:5], 11, v[4:5]
	v_lshlrev_b64 v[6:7], 11, v[6:7]
	v_lshl_add_u64 v[4:5], v[2:3], 0, v[4:5]
	v_lshl_add_u64 v[6:7], v[2:3], 0, v[6:7]
	global_load_dwordx4 v[74:77], v[4:5], off
	global_load_dwordx4 v[78:81], v[6:7], off
	v_lshl_add_u64 v[4:5], s[94:95], 0, v[154:155]
	v_lshl_add_u64 v[6:7], s[94:95], 0, v[156:157]
	s_lshl_b32 s72, s77, 20
	s_lshl_b64 s[82:83], s[82:83], 14
	v_lshlrev_b64 v[4:5], 11, v[4:5]
	v_lshlrev_b64 v[6:7], 11, v[6:7]
	s_add_u32 s77, s68, s82
	v_lshl_add_u64 v[4:5], v[2:3], 0, v[4:5]
	v_lshl_add_u64 v[2:3], v[2:3], 0, v[6:7]
	s_addc_u32 s93, s69, s83
	s_lshl_b64 s[82:83], s[96:97], 1
	global_load_dwordx4 v[82:85], v[4:5], off
	global_load_dwordx4 v[86:89], v[2:3], off
	s_add_u32 s82, s77, s82
	v_or_b32_e32 v2, s72, v196
	s_addc_u32 s83, s93, s83
	v_lshlrev_b32_e32 v2, 1, v2
	v_mov_b32_e32 v3, v145
	v_or_b32_e32 v4, s72, v197
	v_lshl_add_u64 v[2:3], s[82:83], 0, v[2:3]
	v_mov_b32_e32 v165, v145
	v_lshlrev_b32_e32 v4, 1, v4
	v_mov_b32_e32 v5, v145
	v_lshl_add_u64 v[2:3], v[2:3], 0, v[164:165]
	v_lshl_add_u64 v[4:5], s[82:83], 0, v[4:5]
	v_mov_b32_e32 v167, v145
	v_lshl_add_u64 v[4:5], v[4:5], 0, v[166:167]
	global_load_dwordx4 v[94:97], v[2:3], off
	global_load_dwordx4 v[90:93], v[4:5], off
	v_or_b32_e32 v2, s72, v198
	v_lshlrev_b32_e32 v2, 1, v2
	v_mov_b32_e32 v3, v145
	v_or_b32_e32 v4, s72, v199
	v_lshl_add_u64 v[2:3], s[82:83], 0, v[2:3]
	v_mov_b32_e32 v169, v145
	v_lshlrev_b32_e32 v4, 1, v4
	v_mov_b32_e32 v5, v145
	v_lshl_add_u64 v[2:3], v[2:3], 0, v[168:169]
	v_lshl_add_u64 v[4:5], s[82:83], 0, v[4:5]
	v_mov_b32_e32 v171, v145
	v_lshl_add_u64 v[4:5], v[4:5], 0, v[170:171]
	global_load_dwordx4 v[102:105], v[2:3], off
	global_load_dwordx4 v[98:101], v[4:5], off
	v_or_b32_e32 v2, s72, v200
	v_lshlrev_b32_e32 v2, 1, v2
	v_mov_b32_e32 v3, v145
	v_or_b32_e32 v4, s72, v201
	v_lshl_add_u64 v[2:3], s[82:83], 0, v[2:3]
	v_mov_b32_e32 v173, v145
	v_lshlrev_b32_e32 v4, 1, v4
	v_mov_b32_e32 v5, v145
	v_lshl_add_u64 v[2:3], v[2:3], 0, v[172:173]
	v_lshl_add_u64 v[4:5], s[82:83], 0, v[4:5]
	v_mov_b32_e32 v175, v145
	v_lshl_add_u64 v[4:5], v[4:5], 0, v[174:175]
	global_load_dwordx4 v[110:113], v[2:3], off
	global_load_dwordx4 v[106:109], v[4:5], off
	s_cmp_lg_u32 s58, 0
	s_cselect_b32 s58, s81, 0
	s_cmp_lt_i32 s80, s58
	s_cbranch_scc1 .LBB0_552
	s_sub_i32 s72, s80, s58
	v_or_b32_e32 v2, s72, v142
	v_lshrrev_b32_e32 v27, 1, v2
	v_lshl_add_u32 v26, v2, 7, 0
	v_bitop3_b32 v2, v27, v1, 7 bitop3:0x6c
	v_lshl_add_u32 v2, v2, 4, v26
	ds_read_b128 v[2:5], v2
	s_lshr_b32 s77, s72, 2
	v_bitop3_b32 v6, s77, v142, v1 bitop3:0x36
	v_lshlrev_b32_e32 v30, 3, v6
	v_bitop3_b32 v6, v27, v143, 7 bitop3:0x6c
	v_lshl_add_u32 v6, v6, 4, v26
	ds_read_b128 v[18:21], v6
	v_or_b32_e32 v28, s77, v1
	s_waitcnt vmcnt(23) lgkmcnt(1)
	v_mfma_f32_32x32x16_bf16 v[2:17], v[2:5], v[114:117], 0
	v_bitop3_b32 v22, v28, v142, 2 bitop3:0x36
	v_lshlrev_b32_e32 v32, 3, v22
	v_bitop3_b32 v22, v28, v142, 4 bitop3:0x36
	v_lshlrev_b32_e32 v38, 3, v22
	v_bitop3_b32 v22, v27, v147, 7 bitop3:0x6c
	v_lshl_add_u32 v22, v22, 4, v26
	ds_read_b128 v[22:25], v22
	s_waitcnt vmcnt(22) lgkmcnt(1)
	v_mfma_f32_32x32x16_bf16 v[2:17], v[18:21], v[118:121], v[2:17]
	v_bitop3_b32 v18, v28, v142, 6 bitop3:0x36
	v_lshlrev_b32_e32 v39, 3, v18
	v_bitop3_b32 v18, v27, v149, 7 bitop3:0x6c
	v_lshl_add_u32 v18, v18, 4, v26
	ds_read_b128 v[26:29], v18
	v_add_u32_e32 v31, v202, v30
	v_add_u32_e32 v34, v202, v38
	s_waitcnt vmcnt(21) lgkmcnt(1)
	v_mfma_f32_32x32x16_bf16 v[2:17], v[22:25], v[122:125], v[2:17]
	v_add_u32_e32 v36, v202, v39
	v_add_u32_e32 v22, v203, v30
	v_add_u32_e32 v24, v203, v38
	v_add_u32_e32 v33, v202, v32
	ds_read_b64 v[18:19], v31 offset:49152
	ds_read_b64 v[20:21], v33 offset:49152
	ds_read_b64 v[34:35], v34 offset:49152
	ds_read_b64 v[36:37], v36 offset:49152
	v_add_u32_e32 v23, v203, v32
	v_add_u32_e32 v25, v203, v39
	s_waitcnt vmcnt(20) lgkmcnt(4)
	v_mfma_f32_32x32x16_bf16 v[2:17], v[26:29], v[126:129], v[2:17]
	ds_read_b64 v[42:43], v22 offset:24576
	ds_read_b64 v[44:45], v23 offset:24576
	ds_read_b64 v[38:39], v24 offset:24576
	ds_read_b64 v[40:41], v25 offset:24576
	v_and_b32_e32 v48, 64, v216
	v_add_u32_e32 v48, 64, v48
	s_mov_b64 s[80:81], 0
	s_nop 4
	v_min_f32_e64 v3, -v3, s98
	v_exp_f32_e32 v3, v3
	v_min_f32_e64 v4, -v4, s98
	v_exp_f32_e32 v24, v4
	v_add_f32_e32 v22, 1.0, v3
	v_min_f32_e64 v4, -v5, s98
	v_rcp_f32_e32 v22, v22
	v_exp_f32_e32 v5, v4
	v_add_f32_e32 v4, 1.0, v24
	v_mul_f32_e32 v3, v3, v22
	v_rcp_f32_e32 v25, v4
	v_cndmask_b32_e64 v4, 1.0, v3, s[16:17]
	v_add_f32_e32 v3, 1.0, v5
	v_min_f32_e64 v2, -v2, s98
	v_rcp_f32_e32 v3, v3
	v_exp_f32_e32 v2, v2
	v_mul_f32_e32 v24, v24, v25
	v_cndmask_b32_e64 v46, 1.0, v24, s[18:19]
	v_mul_f32_e32 v5, v5, v3
	v_cndmask_b32_e64 v24, 0, v3, s[20:21]
	v_min_f32_e64 v3, -v6, s98
	v_min_f32_e64 v6, -v7, s98
	v_add_f32_e32 v26, 1.0, v2
	v_exp_f32_e32 v3, v3
	v_rcp_f32_e32 v26, v26
	v_exp_f32_e32 v7, v6
	v_add_f32_e32 v6, 1.0, v3
	v_cndmask_b32_e64 v22, 0, v22, s[16:17]
	v_mul_f32_e32 v2, v2, v26
	v_cndmask_b32_e64 v23, 0, v26, s[14:15]
	v_rcp_f32_e32 v26, v6
	v_cndmask_b32_e64 v6, 1.0, v5, s[20:21]
	v_add_f32_e32 v5, 1.0, v7
	v_rcp_f32_e32 v5, v5
	v_mul_f32_e32 v3, v3, v26
	v_cndmask_b32_e64 v3, 1.0, v3, s[22:23]
	v_cndmask_b32_e64 v2, 1.0, v2, s[14:15]
	v_mul_f32_e32 v7, v7, v5
	v_cndmask_b32_e64 v27, 0, v5, s[24:25]
	v_min_f32_e64 v5, -v8, s98
	v_min_f32_e64 v8, -v9, s98
	v_exp_f32_e32 v5, v5
	v_exp_f32_e32 v8, v8
	v_cndmask_b32_e64 v28, 1.0, v7, s[24:25]
	v_add_f32_e32 v9, 1.0, v5
	v_rcp_f32_e32 v9, v9
	v_add_f32_e32 v7, 1.0, v8
	v_rcp_f32_e32 v7, v7
	v_mul_f32_e32 v3, v3, v28
	v_mul_f32_e32 v5, v5, v9
	v_cndmask_b32_e64 v30, 1.0, v5, s[26:27]
	v_mul_f32_e32 v5, v8, v7
	v_min_f32_e64 v8, -v11, s98
	v_cndmask_b32_e64 v31, 0, v7, s[28:29]
	v_min_f32_e64 v7, -v10, s98
	v_exp_f32_e32 v8, v8
	v_exp_f32_e32 v7, v7
	v_cndmask_b32_e64 v10, 1.0, v5, s[28:29]
	v_cndmask_b32_e64 v29, 0, v9, s[26:27]
	v_add_f32_e32 v5, 1.0, v8
	v_add_f32_e32 v9, 1.0, v7
	v_rcp_f32_e32 v5, v5
	v_rcp_f32_e32 v9, v9
	v_cndmask_b32_e64 v25, 0, v25, s[18:19]
	v_cndmask_b32_e64 v26, 0, v26, s[22:23]
	v_mul_f32_e32 v8, v8, v5
	v_cndmask_b32_e64 v51, 0, v5, s[34:35]
	v_min_f32_e64 v5, -v12, s98
	v_mul_f32_e32 v7, v7, v9
	v_cndmask_b32_e64 v50, 0, v9, s[30:31]
	v_min_f32_e64 v9, -v13, s98
	v_exp_f32_e32 v5, v5
	v_exp_f32_e32 v9, v9
	v_cndmask_b32_e64 v12, 1.0, v8, s[34:35]
	v_add_f32_e32 v11, 1.0, v5
	v_rcp_f32_e32 v11, v11
	v_add_f32_e32 v8, 1.0, v9
	v_rcp_f32_e32 v8, v8
	v_cndmask_b32_e64 v7, 1.0, v7, s[30:31]
	v_mul_f32_e32 v5, v5, v11
	v_cndmask_b32_e64 v52, 0, v11, s[36:37]
	v_cndmask_b32_e64 v11, 1.0, v5, s[36:37]
	v_mul_f32_e32 v5, v9, v8
	v_min_f32_e64 v9, -v15, s98
	v_exp_f32_e32 v9, v9
	v_cndmask_b32_e64 v15, 1.0, v5, s[38:39]
	v_cndmask_b32_e64 v13, 0, v8, s[38:39]
	v_min_f32_e64 v8, -v14, s98
	v_add_f32_e32 v5, 1.0, v9
	v_rcp_f32_e32 v5, v5
	v_exp_f32_e32 v8, v8
	v_mul_f32_e32 v7, v7, v12
	v_mul_f32_e32 v9, v9, v5
	v_cndmask_b32_e64 v32, 0, v5, s[42:43]
	v_min_f32_e64 v5, -v16, s98
	v_min_f32_e64 v16, -v17, s98
	v_exp_f32_e32 v5, v5
	v_exp_f32_e32 v16, v16
	v_add_f32_e32 v14, 1.0, v8
	v_add_f32_e32 v17, 1.0, v5
	v_rcp_f32_e32 v17, v17
	v_add_f32_e32 v33, 1.0, v16
	v_rcp_f32_e32 v33, v33
	v_rcp_f32_e32 v14, v14
	v_mul_f32_e32 v5, v5, v17
	v_cndmask_b32_e64 v47, 1.0, v5, s[44:45]
	v_mul_f32_e32 v5, v16, v33
	v_mul_f32_e32 v8, v8, v14
	v_cndmask_b32_e64 v16, 0, v33, s[46:47]
	v_cndmask_b32_e64 v33, 1.0, v5, s[46:47]
	v_xor_b32_e32 v5, 32, v216
	v_cndmask_b32_e64 v8, 1.0, v8, s[40:41]
	v_cndmask_b32_e64 v9, 1.0, v9, s[42:43]
	v_cmp_lt_i32_e32 vcc, v5, v48
	v_mul_f32_e32 v8, v8, v9
	v_mul_f32_e32 v48, v47, v33
	v_cndmask_b32_e32 v5, v216, v5, vcc
	v_lshlrev_b32_e32 v163, 2, v5
	v_mul_f32_e32 v8, v8, v48
	ds_bpermute_b32 v48, v163, v8
	v_mul_f32_e32 v49, v11, v15
	v_mul_f32_e32 v5, v30, v10
	v_mul_f32_e32 v7, v7, v49
	v_mul_f32_e32 v3, v3, v5
	ds_bpermute_b32 v53, v163, v7
	ds_bpermute_b32 v5, v163, v3
	s_waitcnt lgkmcnt(2)
; __device__ __forceinline__ void attn_phase(LAS unsigned char* lds, const bf16_t* Q, const bf16_t* Kb, const bf16_t* VT, const bf16_t* Zs, bf16_t* OZ, int vcu, int G) {
;     ...
;         int kt = qb; bool done = false;
;     ...
;             ATT_TILE(true)
;             if (__all(carry < STOP)) { done = true; break; }
	v_cndmask_b32_e64 v49, 1.0, v48, s[0:1]
	v_mul_f32_e32 v33, v33, v49
	v_mul_f32_e32 v47, v47, v33
	v_mul_f32_e32 v54, v9, v47
	v_mul_f32_e32 v57, v32, v47
	v_mul_f32_e32 v47, v8, v48
	s_waitcnt lgkmcnt(1)
	v_mul_f32_e32 v7, v7, v53
	v_pk_mul_f32 v[8:9], v[46:47], v[6:7]
	s_waitcnt lgkmcnt(0)
	v_pk_mul_f32 v[2:3], v[2:3], v[4:5]
	v_mul_f32_e32 v55, v16, v49
	v_pk_mul_f32 v[48:49], v[2:3], v[8:9]
	ds_bpermute_b32 v58, v163, v48
	v_mul_f32_e32 v2, v9, v5
	v_cndmask_b32_e64 v2, v9, v2, s[0:1]
	v_mul_f32_e32 v3, v10, v2
	v_mul_f32_e32 v8, v31, v2
	s_waitcnt lgkmcnt(0)
	v_mul_f32_e32 v2, v49, v58
	v_cndmask_b32_e64 v2, v49, v2, s[0:1]
	v_mul_f32_e32 v5, v30, v3
	v_mul_f32_e32 v9, v29, v3
	v_mul_f32_e32 v3, v6, v2
	v_mul_f32_e32 v6, v46, v3
	v_mul_f32_e32 v4, v4, v6
	v_mul_f32_e32 v10, v24, v2
	v_mul_f32_e32 v2, v22, v6
	v_mul_f32_e32 v6, v47, v53
	v_mul_f32_e32 v7, v28, v5
	v_cndmask_b32_e64 v6, v47, v6, s[0:1]
	v_mul_f32_e32 v5, v27, v5
	v_mul_f32_e32 v7, v26, v7
	v_mul_f32_e32 v3, v25, v3
	v_mul_f32_e32 v4, v23, v4
	v_mul_f32_e32 v47, v15, v6
	v_cndmask_b32_e64 v14, 0, v14, s[40:41]
	v_cndmask_b32_e64 v17, 0, v17, s[44:45]
	v_cvt_pk_bf16_f32 v2, v4, v2
	v_cvt_pk_bf16_f32 v3, v3, v10
	v_cvt_pk_bf16_f32 v4, v7, v5
	v_cvt_pk_bf16_f32 v5, v9, v8
	v_mul_f32_e32 v53, v11, v47
	v_mul_f32_e32 v56, v17, v33
	v_mfma_f32_32x32x16_bf16 v[18:33], v[18:21], v[2:5], 0
	v_mul_f32_e32 v46, v14, v54
	v_mul_f32_e32 v54, v12, v53
	v_mul_f32_e32 v59, v13, v6
	v_mfma_f32_32x32x16_bf16 v[2:17], v[42:45], v[2:5], 0
	v_mul_f32_e32 v43, v52, v47
	v_mul_f32_e32 v42, v51, v53
	v_mul_f32_e32 v44, v50, v54
	v_cvt_pk_bf16_f32 v42, v44, v42
	v_cvt_pk_bf16_f32 v43, v43, v59
	v_cvt_pk_bf16_f32 v44, v46, v57
	v_cvt_pk_bf16_f32 v45, v56, v55
	s_nop 1
	v_mfma_f32_32x32x16_bf16 v[18:33], v[34:37], v[42:45], v[18:33]
	v_mul_f32_e32 v34, v48, v58
	v_mul_f32_e32 v131, v34, v49
	v_cmp_gt_f32_e32 vcc, s88, v131
	s_cmp_eq_u64 vcc, exec
	v_mfma_f32_32x32x16_bf16 v[2:17], v[38:41], v[42:45], v[2:17]
	s_cbranch_scc1 .LBB0_553
	s_cmp_eq_u32 s90, 0
	s_cbranch_scc1 .LBB0_556
	s_lshl_b32 s72, s59, 8
	s_lshl_b32 s77, s59, 15
	s_sub_i32 s59, s72, 32
	v_add_u32_e32 v34, s72, v204
	s_lshl_b32 s72, s58, 7
	s_sub_i32 s72, s77, s72
	s_add_i32 s93, s86, s91
	v_subrev_u32_e32 v165, s58, v34
	v_add_u32_e32 v167, s72, v205
	s_sub_i32 s77, s59, s58
	s_branch .LBB0_545

; __device__ __forceinline__ void attn_phase(LAS unsigned char* lds, const bf16_t* Q, const bf16_t* Kb, const bf16_t* VT, const bf16_t* Zs, bf16_t* OZ, int vcu, int G) {
;     ...
;         int kt = qb; bool done = false;
;     ...
;             ATT_TILE(true)
.LBB0_545:
	s_nop 7
	v_mov_b64_e32 v[48:49], v[16:17]
	v_mov_b64_e32 v[64:65], v[32:33]
	s_add_i32 s72, s87, s59
	v_mov_b32_e32 v195, v131
	v_mov_b64_e32 v[46:47], v[14:15]
	v_mov_b64_e32 v[44:45], v[12:13]
	v_mov_b64_e32 v[42:43], v[10:11]
	v_mov_b64_e32 v[40:41], v[8:9]
	v_mov_b64_e32 v[38:39], v[6:7]
	v_mov_b64_e32 v[36:37], v[4:5]
	v_mov_b64_e32 v[34:35], v[2:3]
	v_mov_b64_e32 v[62:63], v[30:31]
	v_mov_b64_e32 v[60:61], v[28:29]
	v_mov_b64_e32 v[58:59], v[26:27]
	v_mov_b64_e32 v[56:57], v[24:25]
	v_mov_b64_e32 v[54:55], v[22:23]
	v_mov_b64_e32 v[52:53], v[20:21]
	v_mov_b64_e32 v[50:51], v[18:19]
	s_cmp_lt_i32 s72, s58
	s_mov_b32 s72, s93
	s_cbranch_scc1 .LBB0_544
; __device__ __forceinline__ void attn_phase(LAS unsigned char* lds, const bf16_t* Q, const bf16_t* Kb, const bf16_t* VT, const bf16_t* Zs, bf16_t* OZ, int vcu, int G) {
;     ...
;         int kt = qb; bool done = false;
;     ...
;             ATT_TILE(true)
	v_add_u32_e32 v2, s87, v165
	v_lshrrev_b32_e32 v26, 1, v2
	v_bitop3_b32 v2, v26, v1, 7 bitop3:0x6c
	v_lshl_add_u32 v2, v2, 4, v167
	ds_read_b128 v[2:5], v2
	s_add_i32 s80, s87, s77
	s_lshr_b32 s80, s80, 2
	v_bitop3_b32 v6, s80, v142, v1 bitop3:0x36
	v_lshlrev_b32_e32 v28, 3, v6
	v_bitop3_b32 v6, v26, v143, 7 bitop3:0x6c
	v_lshl_add_u32 v6, v6, 4, v167
	ds_read_b128 v[18:21], v6
	v_or_b32_e32 v27, s80, v1
	s_waitcnt lgkmcnt(1)
	v_mfma_f32_32x32x16_bf16 v[2:17], v[2:5], v[114:117], 0
	v_bitop3_b32 v22, v27, v142, 2 bitop3:0x36
	v_lshlrev_b32_e32 v30, 3, v22
	v_bitop3_b32 v22, v27, v142, 4 bitop3:0x36
	v_lshlrev_b32_e32 v32, 3, v22
	v_bitop3_b32 v22, v26, v147, 7 bitop3:0x6c
	v_lshl_add_u32 v22, v22, 4, v167
	ds_read_b128 v[22:25], v22
	s_waitcnt lgkmcnt(1)
	v_mfma_f32_32x32x16_bf16 v[2:17], v[18:21], v[118:121], v[2:17]
	v_bitop3_b32 v18, v27, v142, 6 bitop3:0x36
	v_lshlrev_b32_e32 v27, 3, v18
	v_bitop3_b32 v18, v26, v149, 7 bitop3:0x6c
	v_lshl_add_u32 v18, v18, 4, v167
	ds_read_b128 v[18:21], v18
	v_add_u32_e32 v29, v202, v28
	v_add_u32_e32 v132, v202, v27
	s_waitcnt lgkmcnt(1)
	v_mfma_f32_32x32x16_bf16 v[2:17], v[22:25], v[122:125], v[2:17]
	v_add_u32_e32 v22, v203, v28
	v_add_u32_e32 v31, v202, v30
	v_add_u32_e32 v33, v202, v32
	ds_read_b64 v[138:139], v29 offset:49152
	ds_read_b64 v[140:141], v31 offset:49152
	ds_read_b64 v[130:131], v33 offset:49152
	ds_read_b64 v[132:133], v132 offset:49152
	v_add_u32_e32 v23, v203, v30
	v_add_u32_e32 v24, v203, v32
	v_add_u32_e32 v25, v203, v27
	s_waitcnt lgkmcnt(4)
	v_mfma_f32_32x32x16_bf16 v[2:17], v[18:21], v[126:129], v[2:17]
	ds_read_b64 v[218:219], v22 offset:24576
	ds_read_b64 v[220:221], v23 offset:24576
	ds_read_b64 v[134:135], v24 offset:24576
	ds_read_b64 v[136:137], v25 offset:24576
	s_add_i32 s90, s90, -1
	s_nop 6
	v_min_f32_e64 v3, -v3, s98
	v_exp_f32_e32 v3, v3
	v_min_f32_e64 v5, -v5, s98
	v_min_f32_e64 v4, -v4, s98
	v_add_f32_e32 v19, 1.0, v3
	v_exp_f32_e32 v194, v5
	v_min_f32_e64 v5, -v6, s98
	v_rcp_f32_e32 v169, v19
	v_exp_f32_e32 v4, v4
	v_exp_f32_e32 v6, v5
	v_min_f32_e64 v5, -v7, s98
	v_exp_f32_e32 v7, v5
	v_mul_f32_e32 v20, v3, v169
	v_add_f32_e32 v3, 1.0, v4
	v_rcp_f32_e32 v22, v3
	v_add_f32_e32 v3, 1.0, v194
	v_rcp_f32_e32 v24, v3
	v_add_f32_e32 v3, 1.0, v6
	v_rcp_f32_e32 v26, v3
	v_add_f32_e32 v3, 1.0, v7
	v_rcp_f32_e32 v27, v3
	v_min_f32_e64 v3, -v8, s98
	v_exp_f32_e32 v8, v3
	v_min_f32_e64 v3, -v9, s98
	v_exp_f32_e32 v9, v3
	v_add_f32_e32 v3, 1.0, v8
	v_rcp_f32_e32 v28, v3
	v_min_f32_e64 v5, -v12, s98
	v_add_f32_e32 v3, 1.0, v9
	v_rcp_f32_e32 v29, v3
	v_min_f32_e64 v3, -v10, s98
	v_exp_f32_e32 v10, v3
	v_min_f32_e64 v3, -v11, s98
	v_exp_f32_e32 v11, v5
	v_min_f32_e64 v5, -v13, s98
	v_exp_f32_e32 v31, v5
	v_min_f32_e64 v5, -v14, s98
	v_exp_f32_e32 v30, v3
	v_exp_f32_e32 v12, v5
	v_min_f32_e64 v5, -v15, s98
	v_exp_f32_e32 v14, v5
	v_min_f32_e64 v5, -v16, s98
	v_add_f32_e32 v3, 1.0, v10
	v_rcp_f32_e32 v226, v3
	v_add_f32_e32 v3, 1.0, v30
	v_exp_f32_e32 v13, v5
	v_min_f32_e64 v5, -v17, s98
	v_rcp_f32_e32 v228, v3
	v_add_f32_e32 v3, 1.0, v11
	v_rcp_f32_e32 v227, v3
	v_add_f32_e32 v3, 1.0, v31
	v_exp_f32_e32 v15, v5
	v_rcp_f32_e32 v229, v3
	v_add_f32_e32 v3, 1.0, v12
	v_rcp_f32_e32 v230, v3
	v_add_f32_e32 v3, 1.0, v14
	v_rcp_f32_e32 v16, v3
	v_add_f32_e32 v3, 1.0, v13
	v_rcp_f32_e32 v231, v3
	v_add_f32_e32 v3, 1.0, v15
	v_rcp_f32_e32 v17, v3
	v_min_f32_e64 v2, -v2, s98
	v_exp_f32_e32 v2, v2
	v_pk_mul_f32 v[12:13], v[12:13], v[230:231]
	v_pk_mul_f32 v[14:15], v[14:15], v[16:17]
	v_pk_mul_f32 v[6:7], v[6:7], v[26:27]
	v_pk_mul_f32 v[224:225], v[12:13], v[14:15]
	v_add_f32_e32 v18, 1.0, v2
	v_mul_f32_e32 v3, v224, v225
	ds_bpermute_b32 v5, v163, v3
	v_rcp_f32_e32 v18, v18
	v_pk_mul_f32 v[8:9], v[8:9], v[28:29]
	v_pk_mul_f32 v[10:11], v[10:11], v[226:227]
	v_pk_mul_f32 v[232:233], v[30:31], v[228:229]
	v_pk_mul_f32 v[32:33], v[6:7], v[6:7] op_sel_hi:[0,1]
	v_pk_mul_f32 v[222:223], v[8:9], v[8:9] op_sel_hi:[0,1]
	v_pk_mul_f32 v[30:31], v[10:11], v[232:233]
	s_waitcnt lgkmcnt(0)
	v_mul_f32_e32 v25, v3, v5
	v_pk_mul_f32 v[30:31], v[30:31], v[30:31] op_sel:[0,1] op_sel_hi:[1,0]
	v_mov_b32_e32 v3, v33
	v_mov_b32_e32 v19, v223
	ds_bpermute_b32 v23, v163, v30
	v_pk_mul_f32 v[2:3], v[2:3], v[18:19]
	v_mul_f32_e32 v6, v195, v5
	ds_bpermute_b32 v21, v163, v3
	v_cndmask_b32_e64 v225, v195, v6, s[0:1]
	v_mul_f32_e32 v224, v15, v225
	v_mul_f32_e32 v13, v13, v224
	v_mov_b32_e32 v5, v30
	v_mul_f32_e32 v12, v14, v13
	v_pk_mul_f32 v[14:15], v[194:195], v[24:25]
	s_waitcnt lgkmcnt(1)
	v_pk_mul_f32 v[4:5], v[4:5], v[22:23]
	v_mov_b32_e32 v234, v231
	v_mov_b32_e32 v235, v17
	v_mov_b32_e32 v231, v16
	v_pk_mul_f32 v[16:17], v[4:5], v[14:15]
	s_waitcnt lgkmcnt(0)
	v_pk_mul_f32 v[2:3], v[2:3], v[20:21]
	v_mul_f32_e32 v10, v15, v23
	v_pk_mul_f32 v[236:237], v[2:3], v[16:17]
	ds_bpermute_b32 v171, v163, v236
	v_mul_f32_e32 v2, v17, v21
	v_cndmask_b32_e64 v3, v17, v2, s[0:1]
	v_mul_f32_e32 v2, v9, v3
	v_pk_mul_f32 v[16:17], v[28:29], v[2:3]
	v_mul_f32_e32 v3, v8, v2
	s_waitcnt lgkmcnt(0)
	v_mul_f32_e32 v5, v237, v171
	v_mul_f32_e32 v2, v7, v3
	v_cndmask_b32_e64 v7, v237, v5, s[0:1]
	v_mul_f32_e32 v6, v14, v7
	v_mul_f32_e32 v5, v4, v6
	v_pk_mul_f32 v[2:3], v[26:27], v[2:3]
	v_mov_b32_e32 v23, v24
	v_mul_f32_e32 v4, v20, v5
	v_mov_b32_e32 v19, v169
	v_pk_mul_f32 v[234:235], v[234:235], v[224:225]
	v_pk_mul_f32 v[8:9], v[22:23], v[6:7]
	v_pk_mul_f32 v[4:5], v[18:19], v[4:5]
	v_cvt_pk_bf16_f32 v224, v2, v3
	v_cndmask_b32_e64 v3, v15, v10, s[0:1]
	v_cvt_pk_bf16_f32 v222, v4, v5
	v_cvt_pk_bf16_f32 v223, v8, v9
	v_cvt_pk_bf16_f32 v225, v16, v17
	v_mul_f32_e32 v2, v233, v3
	v_mov_b32_e32 v4, v227
	v_mov_b32_e32 v5, v229
	v_mfma_f32_32x32x16_bf16 v[18:33], v[138:141], v[222:225], v[50:65]
	v_mul_f32_e64 v140, v230, v12
	v_mul_f32_e64 v141, v231, v13
	v_mul_f32_e64 v230, v4, v2
	v_mul_f32_e64 v231, v5, v3
	v_mul_f32_e32 v139, v11, v2
	v_mul_f32_e32 v138, v232, v139
	v_mov_b32_e32 v227, v228
	v_pk_mul_f32 v[138:139], v[226:227], v[138:139]
	v_cvt_pk_bf16_f32 v140, v140, v141
	v_mfma_f32_32x32x16_bf16 v[2:17], v[218:221], v[222:225], v[34:49]
	v_cvt_pk_bf16_f32 v138, v138, v139
	v_cvt_pk_bf16_f32 v139, v230, v231
	v_cvt_pk_bf16_f32 v141, v234, v235
	s_nop 1
	v_mfma_f32_32x32x16_bf16 v[18:33], v[130:133], v[138:141], v[18:33]
	v_mul_f32_e32 v130, v236, v171
	v_mul_f32_e32 v131, v130, v237
	v_cmp_gt_f32_e32 vcc, s88, v131
	s_cmp_lg_u64 vcc, exec
	v_mfma_f32_32x32x16_bf16 v[2:17], v[134:137], v[138:141], v[2:17]
	s_cbranch_scc0 .LBB0_548
	s_add_i32 s93, s72, -1
	s_sub_i32 s77, s77, 32
	s_sub_i32 s59, s59, 32
	s_cmp_lt_i32 s93, 2
	s_mov_b32 s94, -1
	v_subrev_u32_e32 v165, 32, v165
	v_add_u32_e32 v167, 0xfffff000, v167
	s_cselect_b64 s[80:81], -1, 0
	s_mov_b64 s[82:83], 0
	s_and_b64 vcc, exec, s[80:81]
	s_cbranch_vccz .LBB0_545
	s_branch .LBB0_549

; __device__ __forceinline__ void attn_phase(LAS unsigned char* lds, const bf16_t* Q, const bf16_t* Kb, const bf16_t* VT, const bf16_t* Zs, bf16_t* OZ, int vcu, int G) {
;     ...
;         int kt = qb; bool done = false;
;     ...
;             ATT_TILE(true)
;             if (__all(carry < STOP)) { done = true; break; }
;         }
;     ...
;             ATT_TILE(false)
;             if (__all(carry < STOP)) break;
.LBB0_555:
	v_lshl_add_u64 v[34:35], v[134:135], 0, s[72:73]
	v_lshlrev_b64 v[34:35], 11, v[34:35]
	v_lshl_add_u64 v[140:141], s[72:73], 1, v[132:133]
	v_lshl_add_u64 v[194:195], v[136:137], 0, v[34:35]
	global_load_dwordx2 v[62:63], v[140:141], off
	global_load_dwordx2 v[64:65], v[140:141], off offset:16
	global_load_dwordx2 v[50:51], v[140:141], off offset:32
	global_load_dwordx2 v[52:53], v[140:141], off offset:48
	global_load_dwordx4 v[34:37], v[194:195], off
	global_load_dwordx4 v[54:57], v[194:195], off offset:32
	global_load_dwordx4 v[58:61], v[194:195], off offset:64
	global_load_dwordx4 v[218:221], v[194:195], off offset:96
	v_add_co_u32_e32 v140, vcc, 0x100000, v140
	s_cmp_eq_u32 s58, s90
	s_nop 0
	v_addc_co_u32_e32 v141, vcc, 0, v141, vcc
	s_cselect_b64 vcc, -1, 0
	s_waitcnt vmcnt(3)
	v_mfma_f32_32x32x16_bf16 v[34:49], v[34:37], v[114:117], 0
	s_waitcnt vmcnt(2)
	v_mfma_f32_32x32x16_bf16 v[34:49], v[54:57], v[118:121], v[34:49]
	s_waitcnt vmcnt(1)
	v_mfma_f32_32x32x16_bf16 v[34:49], v[58:61], v[122:125], v[34:49]
	global_load_dwordx2 v[58:59], v[140:141], off
	global_load_dwordx2 v[60:61], v[140:141], off offset:16
	global_load_dwordx2 v[54:55], v[140:141], off offset:32
	global_load_dwordx2 v[56:57], v[140:141], off offset:48
	s_waitcnt vmcnt(4)
	v_mfma_f32_32x32x16_bf16 v[34:49], v[218:221], v[126:129], v[34:49]
	s_nop 11
	v_min_f32_e64 v34, -v34, s98
	v_min_f32_e64 v35, -v35, s98
	v_min_f32_e64 v36, -v36, s98
	v_min_f32_e64 v37, -v37, s98
	v_min_f32_e64 v38, -v38, s98
	v_min_f32_e64 v39, -v39, s98
	v_min_f32_e64 v40, -v40, s98
	v_min_f32_e64 v41, -v41, s98
	v_min_f32_e64 v42, -v42, s98
	v_min_f32_e64 v43, -v43, s98
	v_min_f32_e64 v44, -v44, s98
	v_min_f32_e64 v45, -v45, s98
	v_min_f32_e64 v46, -v46, s98
	v_min_f32_e64 v47, -v47, s98
	v_min_f32_e64 v48, -v48, s98
	v_min_f32_e64 v49, -v49, s98
	v_exp_f32_e32 v34, v34
	v_exp_f32_e32 v35, v35
	v_exp_f32_e32 v36, v36
	v_exp_f32_e32 v37, v37
	v_exp_f32_e32 v38, v38
	v_exp_f32_e32 v39, v39
	v_exp_f32_e32 v40, v40
	v_exp_f32_e32 v41, v41
	v_exp_f32_e32 v42, v42
	v_exp_f32_e32 v43, v43
	v_exp_f32_e32 v44, v44
	v_exp_f32_e32 v45, v45
	v_exp_f32_e32 v46, v46
	v_exp_f32_e32 v47, v47
	v_exp_f32_e32 v48, v48
	v_exp_f32_e32 v49, v49
	v_add_f32_e32 v130, 1.0, v34
	v_add_f32_e32 v139, 1.0, v35
	v_add_f32_e32 v140, 1.0, v36
	v_add_f32_e32 v141, 1.0, v37
	v_add_f32_e32 v163, 1.0, v38
	v_add_f32_e32 v165, 1.0, v39
	v_add_f32_e32 v167, 1.0, v40
	v_add_f32_e32 v169, 1.0, v41
	v_add_f32_e32 v171, 1.0, v42
	v_add_f32_e32 v173, 1.0, v43
	v_add_f32_e32 v175, 1.0, v44
	v_add_f32_e32 v194, 1.0, v45
	v_add_f32_e32 v195, 1.0, v46
	v_add_f32_e32 v217, 1.0, v47
	v_add_f32_e32 v218, 1.0, v48
	v_add_f32_e32 v219, 1.0, v49
	v_rcp_f32_e32 v130, v130
	v_rcp_f32_e32 v139, v139
	v_rcp_f32_e32 v140, v140
	v_rcp_f32_e32 v141, v141
	v_rcp_f32_e32 v163, v163
	v_rcp_f32_e32 v165, v165
	v_rcp_f32_e32 v167, v167
	v_rcp_f32_e32 v169, v169
	v_rcp_f32_e32 v171, v171
	v_rcp_f32_e32 v173, v173
	v_rcp_f32_e32 v175, v175
	v_rcp_f32_e32 v194, v194
	v_rcp_f32_e32 v195, v195
	v_rcp_f32_e32 v217, v217
	v_rcp_f32_e32 v218, v218
	v_rcp_f32_e32 v219, v219
	v_cndmask_b32_e64 v220, 0, v130, s[14:15]
	v_mul_f32_e32 v34, v34, v130
	v_mul_f32_e32 v35, v35, v139
	v_cndmask_b32_e64 v221, 0, v139, s[16:17]
	v_mul_f32_e32 v36, v36, v140
	v_cndmask_b32_e64 v222, 0, v140, s[18:19]
	v_mul_f32_e32 v37, v37, v141
	v_cndmask_b32_e64 v223, 0, v141, s[20:21]
	v_mul_f32_e32 v38, v38, v163
	v_cndmask_b32_e64 v224, 0, v163, s[22:23]
	v_mul_f32_e32 v39, v39, v165
	v_cndmask_b32_e64 v225, 0, v165, s[24:25]
	v_mul_f32_e32 v40, v40, v167
	v_cndmask_b32_e64 v226, 0, v167, s[26:27]
	v_mul_f32_e32 v41, v41, v169
	v_cndmask_b32_e64 v227, 0, v169, s[28:29]
	v_mul_f32_e32 v42, v42, v171
	v_cndmask_b32_e64 v228, 0, v171, s[30:31]
	v_mul_f32_e32 v43, v43, v173
	v_cndmask_b32_e64 v229, 0, v173, s[34:35]
	v_mul_f32_e32 v44, v44, v175
	v_cndmask_b32_e64 v230, 0, v175, s[36:37]
	v_mul_f32_e32 v45, v45, v194
	v_cndmask_b32_e64 v231, 0, v194, s[38:39]
	v_mul_f32_e32 v46, v46, v195
	v_cndmask_b32_e64 v232, 0, v195, s[40:41]
	v_mul_f32_e32 v47, v47, v217
	v_cndmask_b32_e64 v233, 0, v217, s[42:43]
	v_mul_f32_e32 v48, v48, v218
	v_cndmask_b32_e64 v234, 0, v218, s[44:45]
	v_mul_f32_e32 v49, v49, v219
	v_cndmask_b32_e64 v235, 0, v219, s[46:47]
	v_cndmask_b32_e64 v236, 1.0, v34, s[14:15]
	v_cndmask_b32_e32 v220, v130, v220, vcc
	v_cndmask_b32_e64 v130, 1.0, v35, s[16:17]
	v_cndmask_b32_e32 v139, v139, v221, vcc
	v_cndmask_b32_e64 v221, 1.0, v36, s[18:19]
	v_cndmask_b32_e32 v140, v140, v222, vcc
	v_cndmask_b32_e64 v222, 1.0, v37, s[20:21]
	v_cndmask_b32_e32 v141, v141, v223, vcc
	v_cndmask_b32_e64 v223, 1.0, v38, s[22:23]
	v_cndmask_b32_e32 v163, v163, v224, vcc
	v_cndmask_b32_e64 v224, 1.0, v39, s[24:25]
	v_cndmask_b32_e32 v165, v165, v225, vcc
	v_cndmask_b32_e64 v225, 1.0, v40, s[26:27]
	v_cndmask_b32_e32 v167, v167, v226, vcc
	v_cndmask_b32_e64 v226, 1.0, v41, s[28:29]
	v_cndmask_b32_e32 v169, v169, v227, vcc
	v_cndmask_b32_e64 v227, 1.0, v42, s[30:31]
	v_cndmask_b32_e32 v171, v171, v228, vcc
	v_cndmask_b32_e64 v228, 1.0, v43, s[34:35]
	v_cndmask_b32_e32 v173, v173, v229, vcc
	v_cndmask_b32_e64 v229, 1.0, v44, s[36:37]
	v_cndmask_b32_e32 v175, v175, v230, vcc
	v_cndmask_b32_e64 v230, 1.0, v45, s[38:39]
	v_cndmask_b32_e32 v194, v194, v231, vcc
	v_cndmask_b32_e64 v231, 1.0, v46, s[40:41]
	v_cndmask_b32_e32 v195, v195, v232, vcc
	v_cndmask_b32_e64 v232, 1.0, v47, s[42:43]
	v_cndmask_b32_e32 v217, v217, v233, vcc
	v_cndmask_b32_e64 v233, 1.0, v48, s[44:45]
	v_cndmask_b32_e32 v218, v218, v234, vcc
	v_cndmask_b32_e64 v234, 1.0, v49, s[46:47]
	v_cndmask_b32_e32 v219, v219, v235, vcc
	v_cndmask_b32_e32 v235, v34, v236, vcc
	v_cndmask_b32_e32 v236, v35, v130, vcc
	v_cndmask_b32_e32 v221, v36, v221, vcc
	v_cndmask_b32_e32 v222, v37, v222, vcc
	v_cndmask_b32_e32 v34, v38, v223, vcc
	v_cndmask_b32_e32 v36, v39, v224, vcc
	v_cndmask_b32_e32 v130, v40, v225, vcc
	v_cndmask_b32_e32 v38, v41, v226, vcc
	v_cndmask_b32_e32 v35, v42, v227, vcc
	v_cndmask_b32_e32 v223, v43, v228, vcc
	v_cndmask_b32_e32 v224, v44, v229, vcc
	v_cndmask_b32_e32 v225, v45, v230, vcc
	v_cndmask_b32_e32 v37, v46, v231, vcc
	v_cndmask_b32_e32 v46, v47, v232, vcc
	v_cndmask_b32_e32 v41, v48, v233, vcc
	v_cndmask_b32_e32 v43, v49, v234, vcc
	v_mul_f32_e32 v35, v35, v223
	v_mul_f32_e32 v39, v224, v225
	v_mul_f32_e32 v37, v37, v46
	v_mul_f32_e32 v44, v41, v43
	v_mul_f32_e32 v35, v35, v39
	v_mul_f32_e32 v39, v37, v44
	ds_bpermute_b32 v44, v138, v39
	ds_bpermute_b32 v37, v138, v35
	v_mul_f32_e32 v40, v235, v236
	v_mul_f32_e32 v42, v221, v222
	s_waitcnt lgkmcnt(1)
; __device__ __forceinline__ void attn_phase(LAS unsigned char* lds, const bf16_t* Q, const bf16_t* Kb, const bf16_t* VT, const bf16_t* Zs, bf16_t* OZ, int vcu, int G) {
;     ...
;         int kt = qb; bool done = false;
;     ...
;             ATT_TILE(true)
;             if (__all(carry < STOP)) { done = true; break; }
;         }
;     ...
;             ATT_TILE(false)
;             if (__all(carry < STOP)) break;
	v_mul_f32_e32 v45, v131, v44
	v_mul_f32_e32 v39, v39, v44
	s_waitcnt lgkmcnt(0)
	v_pk_mul_f32 v[34:35], v[34:35], v[36:37]
	v_cndmask_b32_e64 v47, v131, v45, s[0:1]
	v_pk_mul_f32 v[44:45], v[130:131], v[38:39]
	v_mul_f32_e32 v39, v47, v43
	v_pk_mul_f32 v[34:35], v[34:35], v[44:45]
	ds_bpermute_b32 v43, v138, v34
	v_mul_f32_e32 v44, v41, v39
	v_mov_b32_e32 v41, v34
	v_mul_f32_e32 v37, v45, v37
	v_cndmask_b32_e64 v45, v45, v37, s[0:1]
	s_waitcnt lgkmcnt(0)
	v_mul_f32_e32 v34, v35, v43
	v_pk_mul_f32 v[40:41], v[40:41], v[42:43]
	v_cndmask_b32_e64 v37, v35, v34, s[0:1]
	ds_bpermute_b32 v34, v138, v40
	v_mul_f32_e32 v38, v38, v37
	v_mul_f32_e32 v42, v130, v38
	v_mul_f32_e32 v37, v169, v37
	v_mul_f32_e32 v38, v167, v38
	s_waitcnt lgkmcnt(0)
	v_pk_mul_f32 v[40:41], v[40:41], v[34:35]
	v_mul_f32_e32 v36, v36, v42
	v_mul_f32_e32 v34, v41, v34
	v_cndmask_b32_e64 v34, v41, v34, s[0:1]
	v_mul_f32_e32 v35, v222, v34
	v_mul_f32_e32 v42, v165, v42
	v_cvt_pk_bf16_f32 v37, v38, v37
	v_mul_f32_e32 v36, v163, v36
	v_mul_f32_e32 v38, v221, v35
	v_cvt_pk_bf16_f32 v36, v36, v42
	v_mul_f32_e32 v34, v141, v34
	v_mul_f32_e32 v35, v140, v35
	v_mul_f32_e32 v42, v236, v38
	v_mul_f32_e32 v38, v139, v38
	v_cvt_pk_bf16_f32 v35, v35, v34
	v_mul_f32_e32 v34, v220, v42
	v_cvt_pk_bf16_f32 v34, v34, v38
	v_mul_f32_e32 v43, v225, v45
	v_mul_f32_e32 v38, v46, v44
	v_mfma_f32_32x32x16_bf16 v[18:33], v[62:65], v[34:37], v[18:33]
	v_mul_f32_e32 v42, v217, v44
	v_mul_f32_e32 v44, v194, v45
	v_mul_f32_e32 v45, v224, v43
	v_mul_f32_e32 v47, v47, v219
	v_mul_f32_e32 v39, v218, v39
	v_mul_f32_e32 v38, v195, v38
	v_cvt_pk_bf16_f32 v39, v39, v47
	s_waitcnt vmcnt(2)
	v_mfma_f32_32x32x16_bf16 v[2:17], v[58:61], v[34:37], v[2:17]
	v_mul_f32_e32 v34, v175, v43
	v_mul_f32_e32 v35, v223, v45
	v_mul_f32_e32 v36, v173, v45
	v_cvt_pk_bf16_f32 v37, v34, v44
	v_mul_f32_e32 v34, v171, v35
	v_cvt_pk_bf16_f32 v38, v38, v42
	v_cvt_pk_bf16_f32 v36, v34, v36
	v_mul_f32_e32 v131, v40, v41
	v_cmp_gt_f32_e32 vcc, s88, v131
	v_mfma_f32_32x32x16_bf16 v[18:33], v[50:53], v[36:39], v[18:33]
	s_cmp_lg_u64 vcc, exec
	s_cselect_b64 s[78:79], -1, 0
	s_add_i32 s59, s90, -1
	s_cmp_gt_i32 s90, 0
	s_cselect_b64 s[80:81], -1, 0
	s_and_b64 s[78:79], s[80:81], s[78:79]
	s_mov_b32 s90, s59
	s_waitcnt vmcnt(0)
	v_mfma_f32_32x32x16_bf16 v[2:17], v[54:57], v[36:39], v[2:17]
	s_sub_i32 s72, s72, 32
	s_and_b64 vcc, exec, s[78:79]
	s_cbranch_vccnz .LBB0_555
	s_branch .LBB0_539
